# v36 + attention K/V tile DMA issued behind the first K fragment reads of each QK segment
# baseline (speedup 1.0000x reference)
; #define ATT_WAIT(n) asm volatile("s_waitcnt vmcnt(" #n ")" ::: "memory")
; #define ATT_BAR() do { asm volatile("s_waitcnt lgkmcnt(0)" ::: "memory"); __builtin_amdgcn_s_barrier(); asm volatile("" ::: "memory"); } while (0)
; #define ATT_ISSUE_K() attn_issue_k(F, KH + (size_t)ATT_TILE((t + 2 < nt) ? t + 2 : nt - 1) * ATT_KB, lds + b2 * ATT_KB)
; #define ATT_ISSUE_V() attn_issue_v(F, VT + (size_t)ATT_TILE((t + 2 < nt) ? t + 2 : nt - 1) * ATT_VB, lds + ATT_VBASE + b2 * ATT_VB)
; __device__ __forceinline__ void attn_unit(const Frame& F, int h, int qb, const float* qw, bool desc) {
;     ...
;         for (int t = 0; t < nt; ++t) {
;             const int tl = ATT_TILE(t), tlp = ATT_TILE(t - 1);
;             ATT_ISSUE_K(); if (t > 0) { ATT_SMPV(tlp, bp); } ATT_WAIT(8); ATT_BAR();
;             ATT_ISSUE_V(); ATT_QK(tl, b0); ATT_WAIT(7); ATT_BAR();
.LBB0_1013:
	s_lshl_b32 s89, s89, 14
	s_add_u32 s92, s42, s89
	s_addc_u32 s93, s43, 0
	s_lshl_b32 s89, s75, 14
	s_waitcnt vmcnt(8)
	s_add_i32 s89, s89, 0
	v_mov_b32_e32 v2, v164
	s_waitcnt lgkmcnt(0)
	s_barrier
	s_add_i32 s89, s89, 0x12000
	s_add_i32 vcc_lo, s89, s59
	s_add_i32 vcc_hi, s89, s60
	s_add_u32 s98, s92, s14
	s_addc_u32 s99, s93, s15
	s_add_u32 s100, s92, s16
	s_addc_u32 s101, s93, s17
	s_cmp_gt_i32 s90, s70
	s_cbranch_scc1 .Lmy_attn_skipqk_b
	s_mul_i32 s89, s0, 0x6000
	v_add_u32_e32 v2, s89, v174
	v_add_u32_e32 v16, s89, v175
	ds_read_b128 v[4:7], v2
	ds_read_b128 v[8:11], v2 offset:12288
	ds_read_b128 v[12:15], v16
	ds_read_b128 v[186:189], v16 offset:12288
	v_add_u32_e32 v17, s89, v176
	v_add_u32_e32 v185, s89, v177
	ds_read_b128 v[190:193], v17
	ds_read_b128 v[194:197], v17 offset:12288
	ds_read_b128 v[198:201], v185
	ds_read_b128 v[202:205], v185 offset:12288
	ds_read_b128 v[206:209], v2 offset:128
	ds_read_b128 v[210:213], v2 offset:12416
	ds_read_b128 v[214:217], v16 offset:128
	ds_read_b128 v[218:221], v16 offset:12416
	s_mov_b32 m0, vcc_lo
	s_nop 0
	global_load_lds_dwordx4 v164, s[98:99]
	s_mov_b32 m0, vcc_hi
	s_nop 0
	global_load_lds_dwordx4 v164, s[100:101]
	s_waitcnt lgkmcnt(8)
	v_mfma_f32_32x32x16_bf16 v[98:113], v[4:7], v[114:117], 0
	v_mfma_f32_32x32x16_bf16 v[98:113], v[12:15], v[118:121], v[98:113]
	v_mfma_f32_32x32x16_bf16 v[82:97], v[8:11], v[114:117], 0
	v_mfma_f32_32x32x16_bf16 v[82:97], v[186:189], v[118:121], v[82:97]
	ds_read_b128 v[4:7], v17 offset:128
	ds_read_b128 v[8:11], v17 offset:12416
	ds_read_b128 v[12:15], v185 offset:128
	ds_read_b128 v[186:189], v185 offset:12416
	s_waitcnt lgkmcnt(8)
	v_mfma_f32_32x32x16_bf16 v[98:113], v[190:193], v[122:125], v[98:113]
	v_mfma_f32_32x32x16_bf16 v[98:113], v[198:201], v[126:129], v[98:113]
	v_mfma_f32_32x32x16_bf16 v[82:97], v[194:197], v[122:125], v[82:97]
	v_mfma_f32_32x32x16_bf16 v[82:97], v[202:205], v[126:129], v[82:97]
	ds_read_b128 v[190:193], v2 offset:256
	ds_read_b128 v[194:197], v2 offset:12544
	ds_read_b128 v[198:201], v16 offset:256
	ds_read_b128 v[202:205], v16 offset:12544
	s_waitcnt lgkmcnt(8)
	v_mfma_f32_32x32x16_bf16 v[98:113], v[206:209], v[130:133], v[98:113]
	v_mfma_f32_32x32x16_bf16 v[98:113], v[214:217], v[134:137], v[98:113]
	v_mfma_f32_32x32x16_bf16 v[82:97], v[210:213], v[130:133], v[82:97]
	v_mfma_f32_32x32x16_bf16 v[82:97], v[218:221], v[134:137], v[82:97]
	ds_read_b128 v[206:209], v17 offset:256
	ds_read_b128 v[210:213], v17 offset:12544
	ds_read_b128 v[214:217], v185 offset:256
	ds_read_b128 v[218:221], v185 offset:12544
	s_waitcnt lgkmcnt(8)
	v_mfma_f32_32x32x16_bf16 v[98:113], v[4:7], v[138:141], v[98:113]
	v_mfma_f32_32x32x16_bf16 v[98:113], v[12:15], v[142:145], v[98:113]
	v_mfma_f32_32x32x16_bf16 v[82:97], v[8:11], v[138:141], v[82:97]
	v_mfma_f32_32x32x16_bf16 v[82:97], v[186:189], v[142:145], v[82:97]
	s_waitcnt lgkmcnt(4)
	v_mfma_f32_32x32x16_bf16 v[98:113], v[190:193], v[146:149], v[98:113]
	v_mfma_f32_32x32x16_bf16 v[98:113], v[198:201], v[154:157], v[98:113]
	v_mfma_f32_32x32x16_bf16 v[82:97], v[194:197], v[146:149], v[82:97]
	v_mfma_f32_32x32x16_bf16 v[82:97], v[202:205], v[154:157], v[82:97]
	s_waitcnt lgkmcnt(0)
	v_mfma_f32_32x32x16_bf16 v[98:113], v[206:209], v[150:153], v[98:113]
	v_mfma_f32_32x32x16_bf16 v[98:113], v[214:217], v[158:161], v[98:113]
	v_mfma_f32_32x32x16_bf16 v[82:97], v[210:213], v[150:153], v[82:97]
	v_mfma_f32_32x32x16_bf16 v[82:97], v[218:221], v[158:161], v[82:97]
	s_branch .LBB0_1016
.Lmy_attn_skipqk_b:
	s_mov_b32 m0, vcc_lo
	s_nop 0
	global_load_lds_dwordx4 v164, s[98:99]
	s_mov_b32 m0, vcc_hi
	s_nop 0
	global_load_lds_dwordx4 v164, s[100:101]

; #define ATT_WAIT(n) asm volatile("s_waitcnt vmcnt(" #n ")" ::: "memory")
; #define ATT_BAR() do { asm volatile("s_waitcnt lgkmcnt(0)" ::: "memory"); __builtin_amdgcn_s_barrier(); asm volatile("" ::: "memory"); } while (0)
; #define ATT_ISSUE_K() attn_issue_k(F, KH + (size_t)ATT_TILE((t + 2 < nt) ? t + 2 : nt - 1) * ATT_KB, lds + b2 * ATT_KB)
; __device__ __forceinline__ void attn_unit(const Frame& F, int h, int qb, const float* qw, bool desc) {
;     ...
;         for (int t = 0; t < nt; ++t) {
;             const int tl = ATT_TILE(t);
;             ATT_ISSUE_K(); ATT_QK(tl, b0); ATT_WAIT(8); ATT_BAR();
.LBB0_1027:
	s_min_u32 s75, s33, s45
	s_mul_i32 s0, s75, 0x6000
	s_add_u32 s0, s40, s0
	s_addc_u32 s1, s41, 0
	s_mul_i32 s88, s74, 0x6000
	v_mov_b32_e32 v2, v164
	s_add_i32 s88, s88, 0
	s_mov_b32 s98, s0
	s_mov_b32 s99, s1
	s_mov_b32 vcc_lo, s88
	s_cmp_le_u32 s72, s70
	s_cselect_b64 s[0:1], -1, 0
	s_cmp_gt_u32 s72, s70
	s_cbranch_scc1 .Lmy_attn_skipqk_a
	s_mul_i32 s88, s73, 0x6000
	v_add_u32_e32 v2, s88, v174
	v_add_u32_e32 v16, s88, v175
	ds_read_b128 v[4:7], v2
	ds_read_b128 v[8:11], v2 offset:12288
	ds_read_b128 v[12:15], v16
	ds_read_b128 v[180:183], v16 offset:12288
	v_add_u32_e32 v17, s88, v176
	v_add_u32_e32 v179, s88, v177
	ds_read_b128 v[184:187], v17
	ds_read_b128 v[188:191], v17 offset:12288
	ds_read_b128 v[192:195], v179
	ds_read_b128 v[196:199], v179 offset:12288
	ds_read_b128 v[200:203], v2 offset:128
	ds_read_b128 v[204:207], v2 offset:12416
	ds_read_b128 v[208:211], v16 offset:128
	ds_read_b128 v[212:215], v16 offset:12416
	s_add_i32 m0, vcc_lo, s56
	s_add_u32 s100, s98, s8
	s_addc_u32 s101, s99, s9
	global_load_lds_dwordx4 v164, s[100:101]
	s_add_i32 m0, vcc_lo, s57
	s_add_u32 s100, s98, s10
	s_addc_u32 s101, s99, s11
	global_load_lds_dwordx4 v164, s[100:101]
	s_add_i32 m0, vcc_lo, s58
	s_add_u32 s100, s98, s12
	s_addc_u32 s101, s99, s13
	global_load_lds_dwordx4 v164, s[100:101]
	s_waitcnt lgkmcnt(8)
	v_mfma_f32_32x32x16_bf16 v[98:113], v[4:7], v[114:117], 0
	v_mfma_f32_32x32x16_bf16 v[98:113], v[12:15], v[118:121], v[98:113]
	v_mfma_f32_32x32x16_bf16 v[82:97], v[8:11], v[114:117], 0
	v_mfma_f32_32x32x16_bf16 v[82:97], v[180:183], v[118:121], v[82:97]
	ds_read_b128 v[4:7], v17 offset:128
	ds_read_b128 v[8:11], v17 offset:12416
	ds_read_b128 v[12:15], v179 offset:128
	ds_read_b128 v[180:183], v179 offset:12416
	s_waitcnt lgkmcnt(8)
	v_mfma_f32_32x32x16_bf16 v[98:113], v[184:187], v[122:125], v[98:113]
	v_mfma_f32_32x32x16_bf16 v[98:113], v[192:195], v[126:129], v[98:113]
	v_mfma_f32_32x32x16_bf16 v[82:97], v[188:191], v[122:125], v[82:97]
	v_mfma_f32_32x32x16_bf16 v[82:97], v[196:199], v[126:129], v[82:97]
	ds_read_b128 v[184:187], v2 offset:256
	ds_read_b128 v[188:191], v2 offset:12544
	ds_read_b128 v[192:195], v16 offset:256
	ds_read_b128 v[196:199], v16 offset:12544
	s_waitcnt lgkmcnt(8)
	v_mfma_f32_32x32x16_bf16 v[98:113], v[200:203], v[130:133], v[98:113]
	v_mfma_f32_32x32x16_bf16 v[98:113], v[208:211], v[134:137], v[98:113]
	v_mfma_f32_32x32x16_bf16 v[82:97], v[204:207], v[130:133], v[82:97]
	v_mfma_f32_32x32x16_bf16 v[82:97], v[212:215], v[134:137], v[82:97]
	ds_read_b128 v[200:203], v17 offset:256
	ds_read_b128 v[204:207], v17 offset:12544
	ds_read_b128 v[208:211], v179 offset:256
	ds_read_b128 v[212:215], v179 offset:12544
	s_waitcnt lgkmcnt(8)
	v_mfma_f32_32x32x16_bf16 v[98:113], v[4:7], v[138:141], v[98:113]
	v_mfma_f32_32x32x16_bf16 v[98:113], v[12:15], v[142:145], v[98:113]
	v_mfma_f32_32x32x16_bf16 v[82:97], v[8:11], v[138:141], v[82:97]
	v_mfma_f32_32x32x16_bf16 v[82:97], v[180:183], v[142:145], v[82:97]
	s_waitcnt lgkmcnt(4)
	v_mfma_f32_32x32x16_bf16 v[98:113], v[184:187], v[146:149], v[98:113]
	v_mfma_f32_32x32x16_bf16 v[98:113], v[192:195], v[154:157], v[98:113]
	v_mfma_f32_32x32x16_bf16 v[82:97], v[188:191], v[146:149], v[82:97]
	v_mfma_f32_32x32x16_bf16 v[82:97], v[196:199], v[154:157], v[82:97]
	s_waitcnt lgkmcnt(0)
	v_mfma_f32_32x32x16_bf16 v[98:113], v[200:203], v[150:153], v[98:113]
	v_mfma_f32_32x32x16_bf16 v[98:113], v[208:211], v[158:161], v[98:113]
	v_mfma_f32_32x32x16_bf16 v[82:97], v[204:207], v[150:153], v[82:97]
	v_mfma_f32_32x32x16_bf16 v[82:97], v[212:215], v[158:161], v[82:97]
	s_branch .LBB0_1030
.Lmy_attn_skipqk_a:
	s_add_i32 m0, vcc_lo, s56
	s_add_u32 s100, s98, s8
	s_addc_u32 s101, s99, s9
	global_load_lds_dwordx4 v164, s[100:101]
	s_add_i32 m0, vcc_lo, s57
	s_add_u32 s100, s98, s10
	s_addc_u32 s101, s99, s11
	global_load_lds_dwordx4 v164, s[100:101]
	s_add_i32 m0, vcc_lo, s58
	s_add_u32 s100, s98, s12
	s_addc_u32 s101, s99, s13
	global_load_lds_dwordx4 v164, s[100:101]
